# MoBA gate: both halves of each block's k-mean values loaded in one round trip (second half into free fragment registers), q fragment loads before the LUT wait
# baseline (speedup 1.0000x reference)
; DI void attn_job(const Args& a, unsigned char* wsh, LAS unsigned char* wl, int type, int b, int qt, int hd, const int tid) {
;     ...
;         load_lut(lut, glut, bcol, lane);
;         bf16x8 qf[4];
;         const bf16_t* qp = prm + (size_t)(tok0 + t0 + r) * RM_LD + qcol + 8 * h;
; #pragma unroll
;         for (int ks = 0; ks < 4; ++ks) qf[ks] = *(const bf16x8*)(qp + 16 * ks);
;         c.kg = prm + (size_t)tok0 * RM_LD + kcol;
;         c.vg = prt + (size_t)vrow * MTOK + tok0;
;         if (type == 0) {
;             attn_range<0>(c, qf, 0, qt, t0, d00, st, maskrow, h8, 0, 0, false);
;         } else if (type == 1) {
;             const int win = (g == 0) ? 128 : (g == 1 ? 512 : 2048), dmask = (g == 0) ? 0 : (g == 1 ? 3 : 15);
;             int lo = t0 - win; if (lo < 0) lo = 0;
;             attn_range<1>(c, qf, lo >> 5, qt, t0, d00, st, maskrow, h8, win, dmask, false);
;         } else {
;             const int cur = qt >> 3;
;             float gate[7];
;             const float* km = kmean + (size_t)((b * 6 + hd) * 8) * 64 + 8 * h;
; #pragma unroll
;     ...
;     float lt = st.l + __shfl_xor(st.l, 32);
;     if (type == 1) {
;         const float* pp = (const float*)(a.ws + WS_G2) + ((size_t)(tok0 + t0 + r) * 4 + hd) * 68;
;         const f32x2 ml = *(const f32x2*)(pp + 64);
;         const float mn = fmaxf(st.m, ml[0]);
;         const float a1 = __builtin_amdgcn_exp2f(st.m - mn), a2 = __builtin_amdgcn_exp2f(ml[0] - mn);
;         lt = lt * a1 + ml[1] * a2;
; #pragma unroll
;         for (int g4 = 0; g4 < 4; ++g4) {
;             const f32x4 p0 = *(const f32x4*)(pp + 8 * g4 + 4 * h), p1 = *(const f32x4*)(pp + 32 + 8 * g4 + 4 * h);
; #pragma unroll
;             for (int e = 0; e < 4; ++e) { st.o0[4 * g4 + e] = st.o0[4 * g4 + e] * a1 + p0[e] * a2; st.o1[4 * g4 + e] = st.o1[4 * g4 + e] * a1 + p1[e] * a2; }
;         }
;     }
;     const float inv = 1.0f / lt;
;     bf16_t* op = oabc + (size_t)(tok0 + t0 + r) * 1024 + ocol + 4 * h;
; #pragma unroll
;     for (int g4 = 0; g4 < 4; ++g4) {
;         u32x2 w;
;         w.x = pk2(st.o0[4 * g4] * inv, st.o0[4 * g4 + 1] * inv); w.y = pk2(st.o0[4 * g4 + 2] * inv, st.o0[4 * g4 + 3] * inv);
;         *(u32x2*)(op + 8 * g4) = w;
;         w.x = pk2(st.o1[4 * g4] * inv, st.o1[4 * g4 + 1] * inv); w.y = pk2(st.o1[4 * g4 + 2] * inv, st.o1[4 * g4 + 3] * inv);
;         *(u32x2*)(op + 32 + 8 * g4) = w;
;     }
.LBB0_329:
	s_waitcnt vmcnt(0)
	ds_bpermute_b32 v0, v160, v102
	s_lshl_b32 s2, s6, 1
	v_lshlrev_b64 v[34:35], 11, v[98:99]
	s_ashr_i32 s9, s57, 3
	s_waitcnt lgkmcnt(0)
	v_add_f32_e32 v0, v102, v0
	v_div_scale_f32 v36, s[6:7], v0, v0, 1.0
	v_rcp_f32_e32 v37, v36
	v_div_scale_f32 v38, vcc, 1.0, v0, 1.0
	v_readlane_b32 s6, v253, 26
	v_fma_f32 v39, -v36, v37, 1.0
	v_fmac_f32_e32 v37, v39, v37
	v_mul_f32_e32 v39, v38, v37
	v_fma_f32 v40, -v36, v39, v38
	v_fmac_f32_e32 v39, v40, v37
	v_fma_f32 v36, -v36, v39, v38
	v_readlane_b32 s7, v253, 27
	v_div_fmas_f32 v36, v36, v37, v39
	v_div_fixup_f32 v36, v36, v0, 1.0
	v_lshl_add_u64 v[34:35], s[6:7], 0, v[34:35]
	v_lshl_add_u64 v[100:101], v[34:35], 0, s[2:3]
	v_lshlrev_b32_e32 v0, 1, v142
	v_pk_mul_f32 v[2:3], v[2:3], v[36:37] op_sel_hi:[1,0]
	v_pk_mul_f32 v[4:5], v[4:5], v[36:37] op_sel_hi:[1,0]
	v_lshl_add_u64 v[98:99], v[100:101], 0, v[0:1]
	v_cvt_pk_bf16_f32 v2, v2, v3
	v_cvt_pk_bf16_f32 v3, v4, v5
	global_store_dwordx2 v[98:99], v[2:3], off offset:64
	v_pk_mul_f32 v[2:3], v[22:23], v[36:37] op_sel_hi:[1,0]
	v_pk_mul_f32 v[4:5], v[24:25], v[36:37] op_sel_hi:[1,0]
	v_cvt_pk_bf16_f32 v2, v2, v3
	v_cvt_pk_bf16_f32 v3, v4, v5
	global_store_dwordx2 v[98:99], v[2:3], off offset:16
	v_pk_mul_f32 v[2:3], v[6:7], v[36:37] op_sel_hi:[1,0]
	v_pk_mul_f32 v[4:5], v[8:9], v[36:37] op_sel_hi:[1,0]
	v_cvt_pk_bf16_f32 v2, v2, v3
	v_cvt_pk_bf16_f32 v3, v4, v5
	global_store_dwordx2 v[98:99], v[2:3], off offset:80
	v_pk_mul_f32 v[2:3], v[26:27], v[36:37] op_sel_hi:[1,0]
	v_pk_mul_f32 v[4:5], v[28:29], v[36:37] op_sel_hi:[1,0]
	v_cvt_pk_bf16_f32 v2, v2, v3
	v_cvt_pk_bf16_f32 v3, v4, v5
	global_store_dwordx2 v[98:99], v[2:3], off offset:32
	v_pk_mul_f32 v[2:3], v[10:11], v[36:37] op_sel_hi:[1,0]
	v_pk_mul_f32 v[4:5], v[12:13], v[36:37] op_sel_hi:[1,0]
	v_cvt_pk_bf16_f32 v2, v2, v3
	v_cvt_pk_bf16_f32 v3, v4, v5
	global_store_dwordx2 v[98:99], v[2:3], off offset:96
	v_pk_mul_f32 v[2:3], v[30:31], v[36:37] op_sel_hi:[1,0]
	v_pk_mul_f32 v[4:5], v[32:33], v[36:37] op_sel_hi:[1,0]
	v_cvt_pk_bf16_f32 v2, v2, v3
	v_cvt_pk_bf16_f32 v3, v4, v5
	s_mov_b32 s6, 0x24000
	global_store_dwordx2 v[98:99], v[2:3], off offset:48
	v_pk_mul_f32 v[2:3], v[14:15], v[36:37] op_sel_hi:[1,0]
	v_add_co_u32_e32 v14, vcc, s6, v96
	s_mov_b32 s6, 0x25000
	s_nop 0
	v_addc_co_u32_e32 v15, vcc, 0, v97, vcc
	v_pk_mul_f32 v[18:19], v[18:19], v[36:37] op_sel_hi:[1,0]
	v_pk_mul_f32 v[20:21], v[20:21], v[36:37] op_sel_hi:[1,0]
	v_pk_mul_f32 v[4:5], v[16:17], v[36:37] op_sel_hi:[1,0]
	v_add_co_u32_e32 v30, vcc, s6, v96
	v_cvt_pk_bf16_f32 v18, v18, v19
	v_cvt_pk_bf16_f32 v19, v20, v21
	v_cvt_pk_bf16_f32 v2, v2, v3
	v_cvt_pk_bf16_f32 v3, v4, v5
	v_addc_co_u32_e32 v31, vcc, 0, v97, vcc
	global_store_dwordx2 v[98:99], v[18:19], off
	global_store_dwordx2 v[98:99], v[2:3], off offset:112
	global_load_dwordx4 v[2:5], v[30:31], off offset:-4096
	s_nop 0
	global_load_dwordx4 v[6:9], v[14:15], off offset:1024
	global_load_dwordx4 v[10:13], v[14:15], off offset:2048
	s_nop 0
	global_load_dwordx4 v[14:17], v[14:15], off offset:3072
	s_nop 0
	global_load_dwordx4 v[18:21], v[30:31], off
	global_load_dwordx4 v[22:25], v[30:31], off offset:1024
	global_load_dwordx4 v[26:29], v[30:31], off offset:2048
	s_nop 0
	global_load_dwordx4 v[30:33], v[30:31], off offset:3072
	v_lshl_add_u64 v[34:35], v[94:95], 0, s[2:3]
	v_add_co_u32_e32 v34, vcc, 0x1000, v34
	s_mul_i32 s6, s56, 6
	s_nop 0
	v_addc_co_u32_e32 v35, vcc, 0, v35, vcc
	s_add_i32 s6, s6, s58
	s_lshl_b32 s6, s6, 3
	s_ashr_i32 s7, s6, 31
	s_lshl_b64 s[6:7], s[6:7], 8
	s_cmp_gt_i32 s9, 0
	v_mov_b32_e32 v0, 0xff800000
	v_mov_b32_e32 v40, 0xff800000
	global_load_dwordx4 v[66:69], v[34:35], off offset:32
	global_load_dwordx4 v[70:73], v[34:35], off
	global_load_dwordx4 v[74:77], v[34:35], off offset:96
	global_load_dwordx4 v[78:81], v[34:35], off offset:64
	s_waitcnt vmcnt(11)
	ds_write_b128 v143, v[2:5] offset:8192
	s_waitcnt vmcnt(10)
	ds_write_b128 v143, v[6:9] offset:9216
	s_waitcnt vmcnt(9)
	ds_write_b128 v143, v[10:13] offset:10240
	s_waitcnt vmcnt(8)
	ds_write_b128 v143, v[14:17] offset:11264
	s_waitcnt vmcnt(7)
	ds_write_b128 v143, v[18:21] offset:12288
	s_waitcnt vmcnt(6)
	ds_write_b128 v143, v[22:25] offset:13312
	s_waitcnt vmcnt(5)
	ds_write_b128 v143, v[26:29] offset:14336
	s_waitcnt vmcnt(4)
	ds_write_b128 v143, v[30:33] offset:15360
	v_lshl_add_u64 v[22:23], v[144:145], 0, s[6:7]
	s_cselect_b64 s[6:7], -1, 0
	s_cmp_lt_i32 s9, 1
	s_waitcnt vmcnt(3)
	v_lshlrev_b32_e32 v33, 16, v66
	s_waitcnt vmcnt(2)
	v_lshlrev_b32_e32 v32, 16, v70
	v_and_b32_e32 v39, 0xffff0000, v66
	v_and_b32_e32 v38, 0xffff0000, v70
	v_lshlrev_b32_e32 v37, 16, v67
	v_lshlrev_b32_e32 v36, 16, v71
	v_and_b32_e32 v35, 0xffff0000, v67
	v_and_b32_e32 v34, 0xffff0000, v71
	v_lshlrev_b32_e32 v31, 16, v68
	v_lshlrev_b32_e32 v30, 16, v72
	v_and_b32_e32 v29, 0xffff0000, v68
	v_and_b32_e32 v28, 0xffff0000, v72
	v_lshlrev_b32_e32 v27, 16, v69
	v_lshlrev_b32_e32 v26, 16, v73
	v_and_b32_e32 v25, 0xffff0000, v69
	v_and_b32_e32 v24, 0xffff0000, v73
	s_waitcnt vmcnt(1)
	v_lshlrev_b32_e32 v19, 16, v74
	s_waitcnt vmcnt(0)
	v_lshlrev_b32_e32 v18, 16, v78
	v_and_b32_e32 v21, 0xffff0000, v74
	v_and_b32_e32 v20, 0xffff0000, v78
	v_lshlrev_b32_e32 v17, 16, v75
	v_lshlrev_b32_e32 v16, 16, v79
	v_and_b32_e32 v15, 0xffff0000, v75
	v_and_b32_e32 v14, 0xffff0000, v79
	v_lshlrev_b32_e32 v13, 16, v76
	v_lshlrev_b32_e32 v12, 16, v80
	v_and_b32_e32 v11, 0xffff0000, v76
	v_and_b32_e32 v10, 0xffff0000, v80
	v_lshlrev_b32_e32 v9, 16, v77
	v_lshlrev_b32_e32 v8, 16, v81
	v_and_b32_e32 v7, 0xffff0000, v77
	v_and_b32_e32 v6, 0xffff0000, v81
	s_cbranch_scc1 .LBB0_331
; DI float bf_lo(unsigned w) { return __uint_as_float(w << 16); }
; DI float bf_hi(unsigned w) { return __uint_as_float(w & 0xFFFF0000u); }
; DI void attn_job(const Args& a, unsigned char* wsh, LAS unsigned char* wl, int type, int b, int qt, int hd, const int tid) {
;     ...
;             for (int n = 0; n < 7; ++n) {
;                 float s = 0.f;
;                 if (n < cur) {
; #pragma unroll
;                     for (int ks = 0; ks < 4; ++ks) {
;                         const f32x4 k0 = *(const f32x4*)(km + n * 64 + 16 * ks), k1 = *(const f32x4*)(km + n * 64 + 16 * ks + 4);
;                         const u32x4 qw = __builtin_bit_cast(u32x4, qf[ks]);
;                         s += bf_lo(qw.x) * k0[0] + bf_hi(qw.x) * k0[1] + bf_lo(qw.y) * k0[2] + bf_hi(qw.y) * k0[3]
;                            + bf_lo(qw.z) * k1[0] + bf_hi(qw.z) * k1[1] + bf_lo(qw.w) * k1[2] + bf_hi(qw.w) * k1[3];
;                     }
;                     s += __shfl_xor(s, 32);
;                 } else s = -__builtin_inff();
;                 gate[n] = s;
	global_load_dwordx4 v[2:5], v[22:23], off offset:16
	global_load_dwordx4 v[40:43], v[22:23], off
	global_load_dwordx4 v[44:47], v[22:23], off offset:80
	global_load_dwordx4 v[48:51], v[22:23], off offset:64
	global_load_dwordx4 v[82:85], v[22:23], off offset:144
	global_load_dwordx4 v[86:89], v[22:23], off offset:128
	global_load_dwordx4 v[90:93], v[22:23], off offset:208
	global_load_dwordx4 v[94:97], v[22:23], off offset:192
	s_waitcnt vmcnt(6)
	v_mov_b32_e32 v52, v40
	s_waitcnt vmcnt(4)
	v_mov_b32_e32 v53, v48
	v_mov_b32_e32 v48, v41
	v_pk_mul_f32 v[40:41], v[48:49], v[38:39]
	v_mov_b32_e32 v48, v42
	v_pk_fma_f32 v[40:41], v[52:53], v[32:33], v[40:41]
	v_mov_b32_e32 v49, v50
	v_pk_fma_f32 v[40:41], v[48:49], v[36:37], v[40:41]
	v_mov_b32_e32 v50, v43
	v_pk_fma_f32 v[40:41], v[50:51], v[34:35], v[40:41]
	v_mov_b32_e32 v42, v2
	v_mov_b32_e32 v43, v44
	v_pk_fma_f32 v[40:41], v[42:43], v[30:31], v[40:41]
	v_mov_b32_e32 v44, v3
	v_pk_fma_f32 v[2:3], v[44:45], v[28:29], v[40:41]
	v_mov_b32_e32 v40, v4
	v_mov_b32_e32 v41, v46
	v_pk_fma_f32 v[2:3], v[40:41], v[26:27], v[2:3]
	v_mov_b32_e32 v46, v5
	v_pk_fma_f32 v[2:3], v[46:47], v[24:25], v[2:3]
	s_nop 0
	v_add_f32_e32 v2, 0, v2
	v_add_f32_e32 v54, v2, v3
	s_waitcnt vmcnt(2)
	v_mov_b32_e32 v52, v86
	s_waitcnt vmcnt(0)
	v_mov_b32_e32 v53, v94
	v_mov_b32_e32 v94, v87
	v_pk_mul_f32 v[86:87], v[94:95], v[20:21]
	v_mov_b32_e32 v94, v88
	v_pk_fma_f32 v[86:87], v[52:53], v[18:19], v[86:87]
	v_mov_b32_e32 v95, v96
	v_pk_fma_f32 v[86:87], v[94:95], v[16:17], v[86:87]
	v_mov_b32_e32 v96, v89
	v_pk_fma_f32 v[86:87], v[96:97], v[14:15], v[86:87]
	v_mov_b32_e32 v88, v82
	v_mov_b32_e32 v89, v90
	v_pk_fma_f32 v[86:87], v[88:89], v[12:13], v[86:87]
	v_mov_b32_e32 v90, v83
	v_pk_fma_f32 v[82:83], v[90:91], v[10:11], v[86:87]
	v_mov_b32_e32 v86, v84
	v_mov_b32_e32 v87, v92
	v_pk_fma_f32 v[82:83], v[86:87], v[8:9], v[82:83]
	v_mov_b32_e32 v92, v85
	v_pk_fma_f32 v[82:83], v[92:93], v[6:7], v[82:83]
	s_nop 0
	v_add_f32_e32 v82, v54, v82
	v_add_f32_e32 v82, v82, v83
	ds_bpermute_b32 v83, v160, v82
	s_waitcnt lgkmcnt(0)
	v_add_f32_e32 v86, v82, v83
	v_mov_b32_e32 v40, v86
.LBB0_331:
	s_cmp_lt_i32 s9, 2
	s_cbranch_scc1 .LBB0_337
	global_load_dwordx4 v[2:5], v[22:23], off offset:272
	global_load_dwordx4 v[42:45], v[22:23], off offset:256
	global_load_dwordx4 v[46:49], v[22:23], off offset:336
	global_load_dwordx4 v[50:53], v[22:23], off offset:320
	global_load_dwordx4 v[82:85], v[22:23], off offset:400
	global_load_dwordx4 v[86:89], v[22:23], off offset:384
	global_load_dwordx4 v[90:93], v[22:23], off offset:464
	global_load_dwordx4 v[94:97], v[22:23], off offset:448
	s_waitcnt vmcnt(6)
	v_mov_b32_e32 v54, v42
	s_waitcnt vmcnt(4)
	v_mov_b32_e32 v55, v50
	v_mov_b32_e32 v50, v43
	v_pk_mul_f32 v[42:43], v[50:51], v[38:39]
	v_mov_b32_e32 v50, v44
	v_pk_fma_f32 v[42:43], v[54:55], v[32:33], v[42:43]
	v_mov_b32_e32 v51, v52
	v_pk_fma_f32 v[42:43], v[50:51], v[36:37], v[42:43]
	v_mov_b32_e32 v52, v45
	v_pk_fma_f32 v[42:43], v[52:53], v[34:35], v[42:43]
	v_mov_b32_e32 v44, v2
	v_mov_b32_e32 v45, v46
	v_pk_fma_f32 v[42:43], v[44:45], v[30:31], v[42:43]
	v_mov_b32_e32 v46, v3
	v_pk_fma_f32 v[2:3], v[46:47], v[28:29], v[42:43]
	v_mov_b32_e32 v42, v4
	v_mov_b32_e32 v43, v48
	v_pk_fma_f32 v[2:3], v[42:43], v[26:27], v[2:3]
	v_mov_b32_e32 v48, v5
	v_pk_fma_f32 v[2:3], v[48:49], v[24:25], v[2:3]
	s_nop 0
	v_add_f32_e32 v0, 0, v2
	v_add_f32_e32 v0, v0, v3
	s_waitcnt vmcnt(2)
	v_mov_b32_e32 v54, v86
	s_waitcnt vmcnt(0)
	v_mov_b32_e32 v55, v94
	v_mov_b32_e32 v94, v87
	v_pk_mul_f32 v[86:87], v[94:95], v[20:21]
	v_mov_b32_e32 v94, v88
	v_pk_fma_f32 v[86:87], v[54:55], v[18:19], v[86:87]
	v_mov_b32_e32 v95, v96
	v_pk_fma_f32 v[86:87], v[94:95], v[16:17], v[86:87]
	v_mov_b32_e32 v96, v89
	v_pk_fma_f32 v[86:87], v[96:97], v[14:15], v[86:87]
	v_mov_b32_e32 v88, v82
	v_mov_b32_e32 v89, v90
	v_pk_fma_f32 v[86:87], v[88:89], v[12:13], v[86:87]
	v_mov_b32_e32 v90, v83
	v_pk_fma_f32 v[82:83], v[90:91], v[10:11], v[86:87]
	v_mov_b32_e32 v86, v84
	v_mov_b32_e32 v87, v92
	v_pk_fma_f32 v[82:83], v[86:87], v[8:9], v[82:83]
	v_mov_b32_e32 v92, v85
	v_pk_fma_f32 v[82:83], v[92:93], v[6:7], v[82:83]
	s_nop 0
	v_add_f32_e32 v0, v0, v82
	v_add_f32_e32 v0, v0, v83
	ds_bpermute_b32 v82, v160, v0
	s_waitcnt lgkmcnt(0)
	v_add_f32_e32 v0, v0, v82
	v_mov_b32_e32 v41, 0xff800000
	s_cmp_lt_i32 s9, 3
	v_mov_b32_e32 v42, 0xff800000
	s_cbranch_scc0 .LBB0_338

; DI float bf_lo(unsigned w) { return __uint_as_float(w << 16); }
; DI float bf_hi(unsigned w) { return __uint_as_float(w & 0xFFFF0000u); }
; DI void attn_job(const Args& a, unsigned char* wsh, LAS unsigned char* wl, int type, int b, int qt, int hd, const int tid) {
;     ...
;             for (int n = 0; n < 7; ++n) {
;                 float s = 0.f;
;                 if (n < cur) {
; #pragma unroll
;                     for (int ks = 0; ks < 4; ++ks) {
;                         const f32x4 k0 = *(const f32x4*)(km + n * 64 + 16 * ks), k1 = *(const f32x4*)(km + n * 64 + 16 * ks + 4);
;                         const u32x4 qw = __builtin_bit_cast(u32x4, qf[ks]);
;                         s += bf_lo(qw.x) * k0[0] + bf_hi(qw.x) * k0[1] + bf_lo(qw.y) * k0[2] + bf_hi(qw.y) * k0[3]
;                            + bf_lo(qw.z) * k1[0] + bf_hi(qw.z) * k1[1] + bf_lo(qw.w) * k1[2] + bf_hi(qw.w) * k1[3];
;                     }
;                     s += __shfl_xor(s, 32);
;                 } else s = -__builtin_inff();
;                 gate[n] = s;
.LBB0_334:
	global_load_dwordx4 v[2:5], v[22:23], off offset:784
	global_load_dwordx4 v[44:47], v[22:23], off offset:768
	global_load_dwordx4 v[48:51], v[22:23], off offset:848
	global_load_dwordx4 v[52:55], v[22:23], off offset:832
	global_load_dwordx4 v[82:85], v[22:23], off offset:912
	global_load_dwordx4 v[86:89], v[22:23], off offset:896
	global_load_dwordx4 v[90:93], v[22:23], off offset:976
	global_load_dwordx4 v[94:97], v[22:23], off offset:960
	s_waitcnt vmcnt(6)
	v_mov_b32_e32 v56, v44
	s_waitcnt vmcnt(4)
	v_mov_b32_e32 v57, v52
	v_mov_b32_e32 v52, v45
	v_pk_mul_f32 v[44:45], v[52:53], v[38:39]
	v_mov_b32_e32 v52, v46
	v_pk_fma_f32 v[44:45], v[56:57], v[32:33], v[44:45]
	v_mov_b32_e32 v53, v54
	v_pk_fma_f32 v[44:45], v[52:53], v[36:37], v[44:45]
	v_mov_b32_e32 v54, v47
	v_pk_fma_f32 v[44:45], v[54:55], v[34:35], v[44:45]
	v_mov_b32_e32 v46, v2
	v_mov_b32_e32 v47, v48
	v_pk_fma_f32 v[44:45], v[46:47], v[30:31], v[44:45]
	v_mov_b32_e32 v48, v3
	v_pk_fma_f32 v[2:3], v[48:49], v[28:29], v[44:45]
	v_mov_b32_e32 v44, v4
	v_mov_b32_e32 v45, v50
	v_pk_fma_f32 v[2:3], v[44:45], v[26:27], v[2:3]
	v_mov_b32_e32 v50, v5
	v_pk_fma_f32 v[2:3], v[50:51], v[24:25], v[2:3]
	s_nop 0
	v_add_f32_e32 v2, 0, v2
	v_add_f32_e32 v41, v2, v3
	s_waitcnt vmcnt(2)
	v_mov_b32_e32 v56, v86
	s_waitcnt vmcnt(0)
	v_mov_b32_e32 v57, v94
	v_mov_b32_e32 v94, v87
	v_pk_mul_f32 v[86:87], v[94:95], v[20:21]
	v_mov_b32_e32 v94, v88
	v_pk_fma_f32 v[86:87], v[56:57], v[18:19], v[86:87]
	v_mov_b32_e32 v95, v96
	v_pk_fma_f32 v[86:87], v[94:95], v[16:17], v[86:87]
	v_mov_b32_e32 v96, v89
	v_pk_fma_f32 v[86:87], v[96:97], v[14:15], v[86:87]
	v_mov_b32_e32 v88, v82
	v_mov_b32_e32 v89, v90
	v_pk_fma_f32 v[86:87], v[88:89], v[12:13], v[86:87]
	v_mov_b32_e32 v90, v83
	v_pk_fma_f32 v[82:83], v[90:91], v[10:11], v[86:87]
	v_mov_b32_e32 v86, v84
	v_mov_b32_e32 v87, v92
	v_pk_fma_f32 v[82:83], v[86:87], v[8:9], v[82:83]
	v_mov_b32_e32 v92, v85
	v_pk_fma_f32 v[82:83], v[92:93], v[6:7], v[82:83]
	s_nop 0
	v_add_f32_e32 v82, v41, v82
	v_add_f32_e32 v82, v82, v83
	ds_bpermute_b32 v83, v160, v82
	s_waitcnt lgkmcnt(0)
	v_add_f32_e32 v41, v82, v83
	v_mov_b32_e32 v43, 0xff800000
	s_cmp_lt_i32 s9, 5
	v_mov_b32_e32 v44, 0xff800000
	s_cbranch_scc0 .LBB0_340

; DI float bf_lo(unsigned w) { return __uint_as_float(w << 16); }
; DI float bf_hi(unsigned w) { return __uint_as_float(w & 0xFFFF0000u); }
; DI void attn_job(const Args& a, unsigned char* wsh, LAS unsigned char* wl, int type, int b, int qt, int hd, const int tid) {
;     ...
;             for (int n = 0; n < 7; ++n) {
;                 float s = 0.f;
;                 if (n < cur) {
; #pragma unroll
;                     for (int ks = 0; ks < 4; ++ks) {
;                         const f32x4 k0 = *(const f32x4*)(km + n * 64 + 16 * ks), k1 = *(const f32x4*)(km + n * 64 + 16 * ks + 4);
;                         const u32x4 qw = __builtin_bit_cast(u32x4, qf[ks]);
;                         s += bf_lo(qw.x) * k0[0] + bf_hi(qw.x) * k0[1] + bf_lo(qw.y) * k0[2] + bf_hi(qw.y) * k0[3]
;                            + bf_lo(qw.z) * k1[0] + bf_hi(qw.z) * k1[1] + bf_lo(qw.w) * k1[2] + bf_hi(qw.w) * k1[3];
;                     }
;                     s += __shfl_xor(s, 32);
;                 } else s = -__builtin_inff();
;                 gate[n] = s;
.LBB0_336:
	global_load_dwordx4 v[2:5], v[22:23], off offset:1296
	global_load_dwordx4 v[46:49], v[22:23], off offset:1280
	global_load_dwordx4 v[50:53], v[22:23], off offset:1360
	global_load_dwordx4 v[54:57], v[22:23], off offset:1344
	global_load_dwordx4 v[82:85], v[22:23], off offset:1424
	global_load_dwordx4 v[86:89], v[22:23], off offset:1408
	global_load_dwordx4 v[90:93], v[22:23], off offset:1488
	global_load_dwordx4 v[94:97], v[22:23], off offset:1472
	s_waitcnt vmcnt(6)
	v_mov_b32_e32 v58, v46
	s_waitcnt vmcnt(4)
	v_mov_b32_e32 v59, v54
	v_mov_b32_e32 v54, v47
	v_pk_mul_f32 v[46:47], v[54:55], v[38:39]
	v_mov_b32_e32 v54, v48
	v_pk_fma_f32 v[46:47], v[58:59], v[32:33], v[46:47]
	v_mov_b32_e32 v55, v56
	v_pk_fma_f32 v[46:47], v[54:55], v[36:37], v[46:47]
	v_mov_b32_e32 v56, v49
	v_pk_fma_f32 v[46:47], v[56:57], v[34:35], v[46:47]
	v_mov_b32_e32 v48, v2
	v_mov_b32_e32 v49, v50
	v_pk_fma_f32 v[46:47], v[48:49], v[30:31], v[46:47]
	v_mov_b32_e32 v50, v3
	v_pk_fma_f32 v[2:3], v[50:51], v[28:29], v[46:47]
	v_mov_b32_e32 v46, v4
	v_mov_b32_e32 v47, v52
	v_pk_fma_f32 v[2:3], v[46:47], v[26:27], v[2:3]
	v_mov_b32_e32 v52, v5
	v_pk_fma_f32 v[2:3], v[52:53], v[24:25], v[2:3]
	s_nop 0
	v_add_f32_e32 v2, 0, v2
	v_add_f32_e32 v43, v2, v3
	s_waitcnt vmcnt(2)
	v_mov_b32_e32 v58, v86
	s_waitcnt vmcnt(0)
	v_mov_b32_e32 v59, v94
	v_mov_b32_e32 v94, v87
	v_pk_mul_f32 v[86:87], v[94:95], v[20:21]
	v_mov_b32_e32 v94, v88
	v_pk_fma_f32 v[86:87], v[58:59], v[18:19], v[86:87]
	v_mov_b32_e32 v95, v96
	v_pk_fma_f32 v[86:87], v[94:95], v[16:17], v[86:87]
	v_mov_b32_e32 v96, v89
	v_pk_fma_f32 v[86:87], v[96:97], v[14:15], v[86:87]
	v_mov_b32_e32 v88, v82
	v_mov_b32_e32 v89, v90
	v_pk_fma_f32 v[86:87], v[88:89], v[12:13], v[86:87]
	v_mov_b32_e32 v90, v83
	v_pk_fma_f32 v[82:83], v[90:91], v[10:11], v[86:87]
	v_mov_b32_e32 v86, v84
	v_mov_b32_e32 v87, v92
	v_pk_fma_f32 v[82:83], v[86:87], v[8:9], v[82:83]
	v_mov_b32_e32 v92, v85
	v_pk_fma_f32 v[82:83], v[92:93], v[6:7], v[82:83]
	s_nop 0
	v_add_f32_e32 v82, v43, v82
	v_add_f32_e32 v82, v82, v83
	ds_bpermute_b32 v83, v160, v82
	s_waitcnt lgkmcnt(0)
	v_add_f32_e32 v43, v82, v83
	s_cmp_lt_i32 s9, 7
	v_mov_b32_e32 v2, 0xff800000
	s_cbranch_scc0 .LBB0_342
	s_branch .LBB0_343

; DI float bf_lo(unsigned w) { return __uint_as_float(w << 16); }
; DI float bf_hi(unsigned w) { return __uint_as_float(w & 0xFFFF0000u); }
; DI void attn_job(const Args& a, unsigned char* wsh, LAS unsigned char* wl, int type, int b, int qt, int hd, const int tid) {
;     ...
;             for (int n = 0; n < 7; ++n) {
;                 float s = 0.f;
;                 if (n < cur) {
; #pragma unroll
;                     for (int ks = 0; ks < 4; ++ks) {
;                         const f32x4 k0 = *(const f32x4*)(km + n * 64 + 16 * ks), k1 = *(const f32x4*)(km + n * 64 + 16 * ks + 4);
;                         const u32x4 qw = __builtin_bit_cast(u32x4, qf[ks]);
;                         s += bf_lo(qw.x) * k0[0] + bf_hi(qw.x) * k0[1] + bf_lo(qw.y) * k0[2] + bf_hi(qw.y) * k0[3]
;                            + bf_lo(qw.z) * k1[0] + bf_hi(qw.z) * k1[1] + bf_lo(qw.w) * k1[2] + bf_hi(qw.w) * k1[3];
;                     }
;                     s += __shfl_xor(s, 32);
;                 } else s = -__builtin_inff();
;                 gate[n] = s;
.LBB0_338:
	global_load_dwordx4 v[2:5], v[22:23], off offset:528
	global_load_dwordx4 v[42:45], v[22:23], off offset:512
	global_load_dwordx4 v[46:49], v[22:23], off offset:592
	global_load_dwordx4 v[50:53], v[22:23], off offset:576
	global_load_dwordx4 v[82:85], v[22:23], off offset:656
	global_load_dwordx4 v[86:89], v[22:23], off offset:640
	global_load_dwordx4 v[90:93], v[22:23], off offset:720
	global_load_dwordx4 v[94:97], v[22:23], off offset:704
	s_waitcnt vmcnt(6)
	v_mov_b32_e32 v54, v42
	s_waitcnt vmcnt(4)
	v_mov_b32_e32 v55, v50
	v_mov_b32_e32 v50, v43
	v_pk_mul_f32 v[42:43], v[50:51], v[38:39]
	v_mov_b32_e32 v50, v44
	v_pk_fma_f32 v[42:43], v[54:55], v[32:33], v[42:43]
	v_mov_b32_e32 v51, v52
	v_pk_fma_f32 v[42:43], v[50:51], v[36:37], v[42:43]
	v_mov_b32_e32 v52, v45
	v_pk_fma_f32 v[42:43], v[52:53], v[34:35], v[42:43]
	v_mov_b32_e32 v44, v2
	v_mov_b32_e32 v45, v46
	v_pk_fma_f32 v[42:43], v[44:45], v[30:31], v[42:43]
	v_mov_b32_e32 v46, v3
	v_pk_fma_f32 v[2:3], v[46:47], v[28:29], v[42:43]
	v_mov_b32_e32 v42, v4
	v_mov_b32_e32 v43, v48
	v_pk_fma_f32 v[2:3], v[42:43], v[26:27], v[2:3]
	v_mov_b32_e32 v48, v5
	v_pk_fma_f32 v[2:3], v[48:49], v[24:25], v[2:3]
	s_nop 0
	v_add_f32_e32 v2, 0, v2
	v_add_f32_e32 v56, v2, v3
	s_waitcnt vmcnt(2)
	v_mov_b32_e32 v54, v86
	s_waitcnt vmcnt(0)
	v_mov_b32_e32 v55, v94
	v_mov_b32_e32 v94, v87
	v_pk_mul_f32 v[86:87], v[94:95], v[20:21]
	v_mov_b32_e32 v94, v88
	v_pk_fma_f32 v[86:87], v[54:55], v[18:19], v[86:87]
	v_mov_b32_e32 v95, v96
	v_pk_fma_f32 v[86:87], v[94:95], v[16:17], v[86:87]
	v_mov_b32_e32 v96, v89
	v_pk_fma_f32 v[86:87], v[96:97], v[14:15], v[86:87]
	v_mov_b32_e32 v88, v82
	v_mov_b32_e32 v89, v90
	v_pk_fma_f32 v[86:87], v[88:89], v[12:13], v[86:87]
	v_mov_b32_e32 v90, v83
	v_pk_fma_f32 v[82:83], v[90:91], v[10:11], v[86:87]
	v_mov_b32_e32 v86, v84
	v_mov_b32_e32 v87, v92
	v_pk_fma_f32 v[82:83], v[86:87], v[8:9], v[82:83]
	v_mov_b32_e32 v92, v85
	v_pk_fma_f32 v[82:83], v[92:93], v[6:7], v[82:83]
	s_nop 0
	v_add_f32_e32 v82, v56, v82
	v_add_f32_e32 v82, v82, v83
	ds_bpermute_b32 v83, v160, v82
	s_waitcnt lgkmcnt(0)
	v_add_f32_e32 v86, v82, v83
	v_mov_b32_e32 v42, v86
	s_cmp_lt_i32 s9, 4
	s_cbranch_scc0 .LBB0_334

; DI float bf_lo(unsigned w) { return __uint_as_float(w << 16); }
; DI float bf_hi(unsigned w) { return __uint_as_float(w & 0xFFFF0000u); }
; DI void attn_job(const Args& a, unsigned char* wsh, LAS unsigned char* wl, int type, int b, int qt, int hd, const int tid) {
;     ...
;             for (int n = 0; n < 7; ++n) {
;                 float s = 0.f;
;                 if (n < cur) {
; #pragma unroll
;                     for (int ks = 0; ks < 4; ++ks) {
;                         const f32x4 k0 = *(const f32x4*)(km + n * 64 + 16 * ks), k1 = *(const f32x4*)(km + n * 64 + 16 * ks + 4);
;                         const u32x4 qw = __builtin_bit_cast(u32x4, qf[ks]);
;                         s += bf_lo(qw.x) * k0[0] + bf_hi(qw.x) * k0[1] + bf_lo(qw.y) * k0[2] + bf_hi(qw.y) * k0[3]
;                            + bf_lo(qw.z) * k1[0] + bf_hi(qw.z) * k1[1] + bf_lo(qw.w) * k1[2] + bf_hi(qw.w) * k1[3];
;                     }
;                     s += __shfl_xor(s, 32);
;                 } else s = -__builtin_inff();
;                 gate[n] = s;
.LBB0_340:
	global_load_dwordx4 v[2:5], v[22:23], off offset:1040
	global_load_dwordx4 v[44:47], v[22:23], off offset:1024
	global_load_dwordx4 v[48:51], v[22:23], off offset:1104
	global_load_dwordx4 v[52:55], v[22:23], off offset:1088
	global_load_dwordx4 v[82:85], v[22:23], off offset:1168
	global_load_dwordx4 v[86:89], v[22:23], off offset:1152
	global_load_dwordx4 v[90:93], v[22:23], off offset:1232
	global_load_dwordx4 v[94:97], v[22:23], off offset:1216
	s_waitcnt vmcnt(6)
	v_mov_b32_e32 v56, v44
	s_waitcnt vmcnt(4)
	v_mov_b32_e32 v57, v52
	v_mov_b32_e32 v52, v45
	v_pk_mul_f32 v[44:45], v[52:53], v[38:39]
	v_mov_b32_e32 v52, v46
	v_pk_fma_f32 v[44:45], v[56:57], v[32:33], v[44:45]
	v_mov_b32_e32 v53, v54
	v_pk_fma_f32 v[44:45], v[52:53], v[36:37], v[44:45]
	v_mov_b32_e32 v54, v47
	v_pk_fma_f32 v[44:45], v[54:55], v[34:35], v[44:45]
	v_mov_b32_e32 v46, v2
	v_mov_b32_e32 v47, v48
	v_pk_fma_f32 v[44:45], v[46:47], v[30:31], v[44:45]
	v_mov_b32_e32 v48, v3
	v_pk_fma_f32 v[2:3], v[48:49], v[28:29], v[44:45]
	v_mov_b32_e32 v44, v4
	v_mov_b32_e32 v45, v50
	v_pk_fma_f32 v[2:3], v[44:45], v[26:27], v[2:3]
	v_mov_b32_e32 v50, v5
	v_pk_fma_f32 v[2:3], v[50:51], v[24:25], v[2:3]
	s_nop 0
	v_add_f32_e32 v2, 0, v2
	v_add_f32_e32 v58, v2, v3
	s_waitcnt vmcnt(2)
	v_mov_b32_e32 v56, v86
	s_waitcnt vmcnt(0)
	v_mov_b32_e32 v57, v94
	v_mov_b32_e32 v94, v87
	v_pk_mul_f32 v[86:87], v[94:95], v[20:21]
	v_mov_b32_e32 v94, v88
	v_pk_fma_f32 v[86:87], v[56:57], v[18:19], v[86:87]
	v_mov_b32_e32 v95, v96
	v_pk_fma_f32 v[86:87], v[94:95], v[16:17], v[86:87]
	v_mov_b32_e32 v96, v89
	v_pk_fma_f32 v[86:87], v[96:97], v[14:15], v[86:87]
	v_mov_b32_e32 v88, v82
	v_mov_b32_e32 v89, v90
	v_pk_fma_f32 v[86:87], v[88:89], v[12:13], v[86:87]
	v_mov_b32_e32 v90, v83
	v_pk_fma_f32 v[82:83], v[90:91], v[10:11], v[86:87]
	v_mov_b32_e32 v86, v84
	v_mov_b32_e32 v87, v92
	v_pk_fma_f32 v[82:83], v[86:87], v[8:9], v[82:83]
	v_mov_b32_e32 v92, v85
	v_pk_fma_f32 v[82:83], v[92:93], v[6:7], v[82:83]
	s_nop 0
	v_add_f32_e32 v82, v58, v82
	v_add_f32_e32 v82, v82, v83
	ds_bpermute_b32 v83, v160, v82
	s_waitcnt lgkmcnt(0)
	v_add_f32_e32 v86, v82, v83
	v_mov_b32_e32 v44, v86
	s_cmp_lt_i32 s9, 6
	s_cbranch_scc0 .LBB0_336

; DI float bf_lo(unsigned w) { return __uint_as_float(w << 16); }
; DI float bf_hi(unsigned w) { return __uint_as_float(w & 0xFFFF0000u); }
; DI void attn_job(const Args& a, unsigned char* wsh, LAS unsigned char* wl, int type, int b, int qt, int hd, const int tid) {
;     ...
;             for (int n = 0; n < 7; ++n) {
;                 float s = 0.f;
;                 if (n < cur) {
; #pragma unroll
;                     for (int ks = 0; ks < 4; ++ks) {
;                         const f32x4 k0 = *(const f32x4*)(km + n * 64 + 16 * ks), k1 = *(const f32x4*)(km + n * 64 + 16 * ks + 4);
;                         const u32x4 qw = __builtin_bit_cast(u32x4, qf[ks]);
;                         s += bf_lo(qw.x) * k0[0] + bf_hi(qw.x) * k0[1] + bf_lo(qw.y) * k0[2] + bf_hi(qw.y) * k0[3]
;                            + bf_lo(qw.z) * k1[0] + bf_hi(qw.z) * k1[1] + bf_lo(qw.w) * k1[2] + bf_hi(qw.w) * k1[3];
;                     }
;                     s += __shfl_xor(s, 32);
;                 } else s = -__builtin_inff();
;                 gate[n] = s;
.LBB0_342:
	global_load_dwordx4 v[2:5], v[22:23], off offset:1552
	global_load_dwordx4 v[46:49], v[22:23], off offset:1536
	global_load_dwordx4 v[50:53], v[22:23], off offset:1616
	global_load_dwordx4 v[54:57], v[22:23], off offset:1600
	global_load_dwordx4 v[82:85], v[22:23], off offset:1680
	global_load_dwordx4 v[86:89], v[22:23], off offset:1664
	global_load_dwordx4 v[90:93], v[22:23], off offset:1744
	global_load_dwordx4 v[94:97], v[22:23], off offset:1728
	s_waitcnt vmcnt(6)
	v_mov_b32_e32 v58, v46
	s_waitcnt vmcnt(4)
	v_mov_b32_e32 v59, v54
	v_mov_b32_e32 v54, v47
	v_pk_mul_f32 v[38:39], v[54:55], v[38:39]
	s_nop 0
	v_pk_fma_f32 v[32:33], v[58:59], v[32:33], v[38:39]
	v_mov_b32_e32 v38, v48
	v_mov_b32_e32 v39, v56
	v_pk_fma_f32 v[32:33], v[38:39], v[36:37], v[32:33]
	v_mov_b32_e32 v56, v49
	v_pk_fma_f32 v[32:33], v[56:57], v[34:35], v[32:33]
	v_mov_b32_e32 v34, v2
	v_mov_b32_e32 v35, v50
	v_pk_fma_f32 v[30:31], v[34:35], v[30:31], v[32:33]
	v_mov_b32_e32 v50, v3
	v_pk_fma_f32 v[2:3], v[50:51], v[28:29], v[30:31]
	v_mov_b32_e32 v28, v4
	v_mov_b32_e32 v29, v52
	v_pk_fma_f32 v[2:3], v[28:29], v[26:27], v[2:3]
	v_mov_b32_e32 v52, v5
	v_pk_fma_f32 v[2:3], v[52:53], v[24:25], v[2:3]
	s_nop 0
	v_add_f32_e32 v2, 0, v2
	v_add_f32_e32 v36, v2, v3
	s_waitcnt vmcnt(2)
	v_mov_b32_e32 v22, v86
	s_waitcnt vmcnt(0)
	v_mov_b32_e32 v23, v94
	v_mov_b32_e32 v94, v87
	v_pk_mul_f32 v[20:21], v[94:95], v[20:21]
	s_nop 0
	v_pk_fma_f32 v[18:19], v[22:23], v[18:19], v[20:21]
	v_mov_b32_e32 v20, v88
	v_mov_b32_e32 v21, v96
	v_pk_fma_f32 v[16:17], v[20:21], v[16:17], v[18:19]
	v_mov_b32_e32 v96, v89
	v_pk_fma_f32 v[14:15], v[96:97], v[14:15], v[16:17]
	v_mov_b32_e32 v16, v82
	v_mov_b32_e32 v17, v90
	v_pk_fma_f32 v[12:13], v[16:17], v[12:13], v[14:15]
	v_mov_b32_e32 v90, v83
	v_pk_fma_f32 v[82:83], v[90:91], v[10:11], v[12:13]
	v_mov_b32_e32 v10, v84
	v_mov_b32_e32 v11, v92
	v_pk_fma_f32 v[82:83], v[10:11], v[8:9], v[82:83]
	v_mov_b32_e32 v92, v85
	v_pk_fma_f32 v[82:83], v[92:93], v[6:7], v[82:83]
	s_nop 0
	v_add_f32_e32 v82, v36, v82
	v_add_f32_e32 v82, v82, v83
	ds_bpermute_b32 v83, v160, v82
	s_waitcnt lgkmcnt(0)
	v_add_f32_e32 v82, v82, v83
	v_mov_b32_e32 v2, v82
